# scan output stores widened: quad transpose of packed bf16 outputs (DPP + v_perm_b32), 4 global_store_dwordx2 per wave per chunk instead of 16 shorts
# baseline (speedup 1.0000x reference)
; __device__ __forceinline__ float bf2f(unsigned h) { return __uint_as_float(h << 16); }
; __device__ __forceinline__ unsigned pk2(float lo, float hi) { const f32x2_t v = {lo, hi}; return __builtin_bit_cast(unsigned, __builtin_convertvector(v, bf16x2_t)); }
; template <bool ISM>
; __device__ void scan_item(const Params& p, int l, int item, unsigned char* lds) {
;     ...
;           for (int j = 0; j < 4; ++j) { const int tl = fq * 4 + j, t = 16 * wid + tl; const float wi = f_wi[t];
;               float inv = 1.f;
;               if (ISM) { const float qn = __shfl(ia[NT - 1][j], lane & 48, 64); const float dn = __shfl(dsum, tl, 64); inv = __builtin_amdgcn_rcpf(fmaxf(fabsf(wi * qn + dn), f_em[t])); }
;               u16* dst = obase + (size_t)od[j];
;               float v[4];
; #pragma unroll
;               for (int n = 0; n < 4; ++n) { v[n] = (wi * ia[n][j] + ib[n][j]) * inv; if (!ISM && dir == 0) v[n] += Dh * bf2f(Vs[t * LDV + n * 16 + fr]); }
;               const unsigned p01 = pk2(v[0], v[1]), p23 = pk2(v[2], v[3]);
;               dst[0] = (u16)(p01 & 0xFFFFu); dst[16] = (u16)(p01 >> 16); dst[32] = (u16)(p23 & 0xFFFFu); dst[48] = (u16)(p23 >> 16); } }
.LBB0_30:
	s_waitcnt vmcnt(23)
	v_mul_f32_e32 v56, 0x3fb8aa3b, v225
	v_exp_f32_e32 v56, v56
	v_mov_b32_e32 v193, v149
	v_lshl_add_u64 v[58:59], v[192:193], 1, s[30:31]
	v_cvt_pk_bf16_f32 v57, v71, v75
	v_cvt_pk_bf16_f32 v60, v79, v87
	v_mov_b32_e32 v246, v57
	v_mov_b32_e32 v247, v60
	v_and_b32_e32 v250, 3, v208
	v_mul_u32_u24_e32 v249, 15, v250
	v_and_b32_e32 v251, 1, v208
	v_mov_b32_e32 v232, 0x5040100
	v_mov_b32_e32 v233, 0x3020706
	v_cmp_eq_u32_e32 vcc, 1, v251
	s_nop 1
	v_cndmask_b32_e32 v248, v232, v233, vcc
	v_cmp_gt_u32_e32 vcc, 2, v250
	s_nop 1
	v_cndmask_b32_e32 v250, v240, v241, vcc
	s_nop 1
	v_mov_b32_dpp v251, v250 quad_perm:[2,3,0,1] row_mask:0xf bank_mask:0xf
	v_cndmask_b32_e32 v232, v251, v240, vcc
	v_cndmask_b32_e32 v233, v241, v251, vcc
	s_nop 1
	v_mov_b32_dpp v234, v232 quad_perm:[1,0,3,2] row_mask:0xf bank_mask:0xf
	v_mov_b32_dpp v235, v233 quad_perm:[1,0,3,2] row_mask:0xf bank_mask:0xf
	v_perm_b32 v234, v234, v232, v248
	v_perm_b32 v235, v235, v233, v248
	v_add_u32_e32 v232, v249, v198
	v_mov_b32_e32 v233, v149
	v_lshl_add_u64 v[232:233], v[232:233], 1, s[30:31]
	global_store_dwordx2 v[232:233], v[234:235], off
	v_cndmask_b32_e32 v250, v242, v243, vcc
	s_nop 1
	v_mov_b32_dpp v251, v250 quad_perm:[2,3,0,1] row_mask:0xf bank_mask:0xf
	v_cndmask_b32_e32 v232, v251, v242, vcc
	v_cndmask_b32_e32 v233, v243, v251, vcc
	s_nop 1
	v_mov_b32_dpp v234, v232 quad_perm:[1,0,3,2] row_mask:0xf bank_mask:0xf
	v_mov_b32_dpp v235, v233 quad_perm:[1,0,3,2] row_mask:0xf bank_mask:0xf
	v_perm_b32 v234, v234, v232, v248
	v_perm_b32 v235, v235, v233, v248
	v_add_u32_e32 v232, v249, v196
	v_mov_b32_e32 v233, v149
	v_lshl_add_u64 v[232:233], v[232:233], 1, s[30:31]
	global_store_dwordx2 v[232:233], v[234:235], off
	v_cndmask_b32_e32 v250, v244, v245, vcc
	s_nop 1
	v_mov_b32_dpp v251, v250 quad_perm:[2,3,0,1] row_mask:0xf bank_mask:0xf
	v_cndmask_b32_e32 v232, v251, v244, vcc
	v_cndmask_b32_e32 v233, v245, v251, vcc
	s_nop 1
	v_mov_b32_dpp v234, v232 quad_perm:[1,0,3,2] row_mask:0xf bank_mask:0xf
	v_mov_b32_dpp v235, v233 quad_perm:[1,0,3,2] row_mask:0xf bank_mask:0xf
	v_perm_b32 v234, v234, v232, v248
	v_perm_b32 v235, v235, v233, v248
	v_add_u32_e32 v232, v249, v194
	v_mov_b32_e32 v233, v149
	v_lshl_add_u64 v[232:233], v[232:233], 1, s[30:31]
	global_store_dwordx2 v[232:233], v[234:235], off
	v_cndmask_b32_e32 v250, v246, v247, vcc
	s_nop 1
	v_mov_b32_dpp v251, v250 quad_perm:[2,3,0,1] row_mask:0xf bank_mask:0xf
	v_cndmask_b32_e32 v232, v251, v246, vcc
	v_cndmask_b32_e32 v233, v247, v251, vcc
	s_nop 1
	v_mov_b32_dpp v234, v232 quad_perm:[1,0,3,2] row_mask:0xf bank_mask:0xf
	v_mov_b32_dpp v235, v233 quad_perm:[1,0,3,2] row_mask:0xf bank_mask:0xf
	v_perm_b32 v234, v234, v232, v248
	v_perm_b32 v235, v235, v233, v248
	v_add_u32_e32 v232, v249, v192
	v_mov_b32_e32 v233, v149
	v_lshl_add_u64 v[232:233], v[232:233], 1, s[30:31]
	global_store_dwordx2 v[232:233], v[234:235], off
	s_waitcnt lgkmcnt(0)
	s_barrier
; __device__ __forceinline__ unsigned pk2(float lo, float hi) { const f32x2_t v = {lo, hi}; return __builtin_bit_cast(unsigned, __builtin_convertvector(v, bf16x2_t)); }
; #define LDS_BAR() do { asm volatile("s_waitcnt lgkmcnt(0)" ::: "memory"); __builtin_amdgcn_s_barrier(); asm volatile("" ::: "memory"); } while (0)
; template <bool ISM>
; __device__ void scan_item(const Params& p, int l, int item, unsigned char* lds) {
;     ...
;         LDS_BAR();
;         {
; #pragma unroll
;           for (int m = 0; m < NT; ++m) st[m] *= decay;
;     ...
;           SCAN_ST(0) SCAN_ST(1) SCAN_ST(2) SCAN_ST(3)
;     ...
; #pragma unroll
;           for (int m = 0; m < NT; ++m) { const unsigned p01 = pk2(st[m][0], st[m][1]), p23 = pk2(st[m][2], st[m][3]);
;               u16* cp = CT + (m * 16 + fq * 4) * LDK + 16 * wid + fr;
;               cp[0] = (u16)(p01 & 0xFFFFu); cp[LDK] = (u16)(p01 >> 16); cp[2 * LDK] = (u16)(p23 & 0xFFFFu); cp[3 * LDK] = (u16)(p23 >> 16); } }
;         LDS_BAR();
	v_pk_mul_f32 v[18:19], v[18:19], v[56:57] op_sel_hi:[1,0]
	v_pk_mul_f32 v[16:17], v[16:17], v[56:57] op_sel_hi:[1,0]
	v_pk_mul_f32 v[22:23], v[22:23], v[56:57] op_sel_hi:[1,0]
	v_pk_mul_f32 v[20:21], v[20:21], v[56:57] op_sel_hi:[1,0]
	v_pk_mul_f32 v[26:27], v[26:27], v[56:57] op_sel_hi:[1,0]
	v_pk_mul_f32 v[24:25], v[24:25], v[56:57] op_sel_hi:[1,0]
	v_pk_mul_f32 v[30:31], v[30:31], v[56:57] op_sel_hi:[1,0]
	v_pk_mul_f32 v[28:29], v[28:29], v[56:57] op_sel_hi:[1,0]
	ds_read_b64_tr_b16 v[72:73], v151 offset:0
	ds_read_b64_tr_b16 v[74:75], v151 offset:0x440
	ds_read_b64_tr_b16 v[68:69], v153 offset:0
	ds_read_b64_tr_b16 v[70:71], v153 offset:0x2c0
	ds_read_b64_tr_b16 v[64:65], v153 offset:32
	ds_read_b64_tr_b16 v[66:67], v153 offset:0x2e0
	ds_read_b64_tr_b16 v[60:61], v153 offset:64
	ds_read_b64_tr_b16 v[62:63], v153 offset:0x300
	ds_read_b64_tr_b16 v[56:57], v153 offset:0x60
	ds_read_b64_tr_b16 v[58:59], v153 offset:0x320
	s_waitcnt lgkmcnt(0)
	s_add_i32 s67, s67, 1
	v_mfma_f32_16x16x32_bf16 v[16:19], v[68:71], v[72:75], v[16:19]
	s_waitcnt vmcnt(6)
	v_mov_b64_e32 v[78:79], v[50:51]
	s_cmpk_lg_i32 s67, 0x42
	v_mov_b64_e32 v[76:77], v[48:49]
	v_mfma_f32_16x16x32_bf16 v[20:23], v[64:67], v[72:75], v[20:23]
	v_mov_b32_e32 v198, v229
	v_mov_b32_e32 v196, v228
	v_mov_b32_e32 v194, v227
	v_mfma_f32_16x16x32_bf16 v[24:27], v[60:63], v[72:75], v[24:27]
	v_mov_b32_e32 v192, v226
	s_waitcnt vmcnt(4)
	v_mov_b32_e32 v225, v146
	v_mfma_f32_16x16x32_bf16 v[28:31], v[56:59], v[72:75], v[28:31]
	ds_read_b64_tr_b16 v[72:73], v151 offset:0x2200
	ds_read_b64_tr_b16 v[74:75], v151 offset:0x2640
	ds_read_b64_tr_b16 v[68:69], v153 offset:0x1600
	ds_read_b64_tr_b16 v[70:71], v153 offset:0x18c0
	ds_read_b64_tr_b16 v[64:65], v153 offset:0x1620
	ds_read_b64_tr_b16 v[66:67], v153 offset:0x18e0
	ds_read_b64_tr_b16 v[60:61], v153 offset:0x1640
	ds_read_b64_tr_b16 v[62:63], v153 offset:0x1900
	ds_read_b64_tr_b16 v[56:57], v153 offset:0x1660
	ds_read_b64_tr_b16 v[58:59], v153 offset:0x1920
	s_waitcnt lgkmcnt(0)
	s_nop 0
	v_mfma_f32_16x16x32_bf16 v[16:19], v[68:71], v[72:75], v[16:19]
	v_mfma_f32_16x16x32_bf16 v[20:23], v[64:67], v[72:75], v[20:23]
	v_mfma_f32_16x16x32_bf16 v[24:27], v[60:63], v[72:75], v[24:27]
	v_mfma_f32_16x16x32_bf16 v[28:31], v[56:59], v[72:75], v[28:31]
	ds_read_b64_tr_b16 v[72:73], v151 offset:0x4400
	ds_read_b64_tr_b16 v[74:75], v151 offset:0x4840
	ds_read_b64_tr_b16 v[68:69], v153 offset:0x2c00
	ds_read_b64_tr_b16 v[70:71], v153 offset:0x2ec0
	ds_read_b64_tr_b16 v[64:65], v153 offset:0x2c20
	ds_read_b64_tr_b16 v[66:67], v153 offset:0x2ee0
	ds_read_b64_tr_b16 v[60:61], v153 offset:0x2c40
	ds_read_b64_tr_b16 v[62:63], v153 offset:0x2f00
	ds_read_b64_tr_b16 v[56:57], v153 offset:0x2c60
	ds_read_b64_tr_b16 v[58:59], v153 offset:0x2f20
	s_waitcnt lgkmcnt(0)
	s_nop 0
	v_mfma_f32_16x16x32_bf16 v[16:19], v[68:71], v[72:75], v[16:19]
	v_mfma_f32_16x16x32_bf16 v[20:23], v[64:67], v[72:75], v[20:23]
	v_mfma_f32_16x16x32_bf16 v[24:27], v[60:63], v[72:75], v[24:27]
	v_mfma_f32_16x16x32_bf16 v[28:31], v[56:59], v[72:75], v[28:31]
	ds_read_b64_tr_b16 v[72:73], v151 offset:0x6600
	ds_read_b64_tr_b16 v[74:75], v151 offset:0x6a40
	ds_read_b64_tr_b16 v[68:69], v153 offset:0x4200
	ds_read_b64_tr_b16 v[70:71], v153 offset:0x44c0
	ds_read_b64_tr_b16 v[64:65], v153 offset:0x4220
	ds_read_b64_tr_b16 v[66:67], v153 offset:0x44e0
	ds_read_b64_tr_b16 v[60:61], v153 offset:0x4240
	ds_read_b64_tr_b16 v[62:63], v153 offset:0x4500
	ds_read_b64_tr_b16 v[56:57], v153 offset:0x4260
	ds_read_b64_tr_b16 v[58:59], v153 offset:0x4520
	s_waitcnt lgkmcnt(0)
	s_nop 0
	v_mfma_f32_16x16x32_bf16 v[16:19], v[68:71], v[72:75], v[16:19]
	v_mov_b64_e32 v[70:71], v[46:47]
	v_mov_b64_e32 v[68:69], v[44:45]
	v_mfma_f32_16x16x32_bf16 v[20:23], v[64:67], v[72:75], v[20:23]
	v_mov_b64_e32 v[66:67], v[42:43]
	v_mov_b64_e32 v[64:65], v[40:41]
	v_mfma_f32_16x16x32_bf16 v[24:27], v[60:63], v[72:75], v[24:27]
	v_mov_b64_e32 v[62:63], v[38:39]
	v_mov_b64_e32 v[60:61], v[36:37]
	v_mfma_f32_16x16x32_bf16 v[28:31], v[56:59], v[72:75], v[28:31]
	v_cvt_pk_bf16_f32 v56, v16, v17
	v_cvt_pk_bf16_f32 v57, v18, v19
	ds_write_b16 v204, v56
	ds_write_b16_d16_hi v204, v56 offset:272
	ds_write_b16 v204, v57 offset:544
	ds_write_b16_d16_hi v204, v57 offset:816
	v_cvt_pk_bf16_f32 v56, v20, v21
	v_cvt_pk_bf16_f32 v57, v22, v23
	ds_write_b16 v204, v56 offset:4352
	ds_write_b16_d16_hi v204, v56 offset:4624
	ds_write_b16 v204, v57 offset:4896
	ds_write_b16_d16_hi v204, v57 offset:5168
	v_cvt_pk_bf16_f32 v56, v24, v25
	v_cvt_pk_bf16_f32 v57, v26, v27
	ds_write_b16 v204, v56 offset:8704
	ds_write_b16_d16_hi v204, v56 offset:8976
	ds_write_b16 v204, v57 offset:9248
	ds_write_b16_d16_hi v204, v57 offset:9520
	v_cvt_pk_bf16_f32 v56, v28, v29
	v_cvt_pk_bf16_f32 v57, v30, v31
	ds_write_b16 v204, v56 offset:13056
	ds_write_b16_d16_hi v204, v56 offset:13328
	ds_write_b16 v204, v57 offset:13600
	ds_write_b16_d16_hi v204, v57 offset:13872
	s_waitcnt lgkmcnt(0)
	s_barrier
	v_mov_b64_e32 v[74:75], v[54:55]
	v_mov_b64_e32 v[58:59], v[34:35]
	v_mov_b64_e32 v[72:73], v[52:53]
	v_mov_b64_e32 v[56:57], v[32:33]
	s_cbranch_scc0 .LBB0_151

; __device__ __forceinline__ float bf2f(unsigned h) { return __uint_as_float(h << 16); }
; template <bool ISM>
; __device__ void scan_item(const Params& p, int l, int item, unsigned char* lds) {
;     ...
;           for (int j = 0; j < 4; ++j) { const int tl = fq * 4 + j, t = 16 * wid + tl; const float wi = f_wi[t];
;               float inv = 1.f;
;               if (ISM) { const float qn = __shfl(ia[NT - 1][j], lane & 48, 64); const float dn = __shfl(dsum, tl, 64); inv = __builtin_amdgcn_rcpf(fmaxf(fabsf(wi * qn + dn), f_em[t])); }
;               u16* dst = obase + (size_t)od[j];
;               float v[4];
; #pragma unroll
;               for (int n = 0; n < 4; ++n) { v[n] = (wi * ia[n][j] + ib[n][j]) * inv; if (!ISM && dir == 0) v[n] += Dh * bf2f(Vs[t * LDV + n * 16 + fr]); }
.LBB0_126:
	v_cvt_pk_bf16_f32 v64, v60, v64
	ds_read_b32 v60, v181
	v_mov_b32_e32 v199, v149
	v_lshl_add_u64 v[88:89], v[198:199], 1, s[30:31]
	v_cvt_pk_bf16_f32 v56, v68, v56
	v_mov_b32_e32 v240, v64
	v_mov_b32_e32 v241, v56
	s_and_b64 vcc, exec, s[18:19]
	s_waitcnt lgkmcnt(0)
	v_fma_f32 v56, v61, v60, v69
	s_cbranch_vccnz .LBB0_130
	ds_read_u16 v61, v224 offset:34992
	s_waitcnt lgkmcnt(0)
	v_lshlrev_b32_e32 v61, 16, v61
	v_fmac_f32_e32 v56, v147, v61
	s_and_b64 vcc, exec, s[18:19]
	v_fma_f32 v61, v65, v60, v73
	s_cbranch_vccz .LBB0_131

; __device__ __forceinline__ float bf2f(unsigned h) { return __uint_as_float(h << 16); }
; template <bool ISM>
; __device__ void scan_item(const Params& p, int l, int item, unsigned char* lds) {
;     ...
;           for (int j = 0; j < 4; ++j) { const int tl = fq * 4 + j, t = 16 * wid + tl; const float wi = f_wi[t];
;               float inv = 1.f;
;               if (ISM) { const float qn = __shfl(ia[NT - 1][j], lane & 48, 64); const float dn = __shfl(dsum, tl, 64); inv = __builtin_amdgcn_rcpf(fmaxf(fabsf(wi * qn + dn), f_em[t])); }
;               u16* dst = obase + (size_t)od[j];
;               float v[4];
; #pragma unroll
;               for (int n = 0; n < 4; ++n) { v[n] = (wi * ia[n][j] + ib[n][j]) * inv; if (!ISM && dir == 0) v[n] += Dh * bf2f(Vs[t * LDV + n * 16 + fr]); }
.LBB0_134:
	v_cvt_pk_bf16_f32 v60, v64, v57
	ds_read_b32 v57, v183
	v_mov_b32_e32 v197, v149
	v_lshl_add_u64 v[68:69], v[196:197], 1, s[30:31]
	v_cvt_pk_bf16_f32 v56, v56, v61
	v_mov_b32_e32 v242, v56
	v_mov_b32_e32 v243, v60
	s_and_b64 vcc, exec, s[18:19]
	s_waitcnt lgkmcnt(0)
	v_fma_f32 v56, v62, v57, v70
	s_cbranch_vccnz .LBB0_138
	ds_read_u16 v60, v224 offset:35168
	s_waitcnt lgkmcnt(0)
	v_lshlrev_b32_e32 v60, 16, v60
	v_fmac_f32_e32 v56, v147, v60
	s_and_b64 vcc, exec, s[18:19]
	v_fma_f32 v60, v66, v57, v74
	s_cbranch_vccz .LBB0_139

; __device__ __forceinline__ float bf2f(unsigned h) { return __uint_as_float(h << 16); }
; template <bool ISM>
; __device__ void scan_item(const Params& p, int l, int item, unsigned char* lds) {
;     ...
;           for (int j = 0; j < 4; ++j) { const int tl = fq * 4 + j, t = 16 * wid + tl; const float wi = f_wi[t];
;               float inv = 1.f;
;               if (ISM) { const float qn = __shfl(ia[NT - 1][j], lane & 48, 64); const float dn = __shfl(dsum, tl, 64); inv = __builtin_amdgcn_rcpf(fmaxf(fabsf(wi * qn + dn), f_em[t])); }
;               u16* dst = obase + (size_t)od[j];
;               float v[4];
; #pragma unroll
;               for (int n = 0; n < 4; ++n) { v[n] = (wi * ia[n][j] + ib[n][j]) * inv; if (!ISM && dir == 0) v[n] += Dh * bf2f(Vs[t * LDV + n * 16 + fr]); }
.LBB0_142:
	v_cvt_pk_bf16_f32 v58, v56, v60
	ds_read_b32 v56, v185
	v_mov_b32_e32 v195, v149
	v_lshl_add_u64 v[64:65], v[194:195], 1, s[30:31]
	s_and_b64 vcc, exec, s[18:19]
	v_cvt_pk_bf16_f32 v57, v61, v57
	s_waitcnt lgkmcnt(0)
	v_fmac_f32_e32 v71, v63, v56
	v_mov_b32_e32 v244, v58
	v_mov_b32_e32 v245, v57
	s_cbranch_vccnz .LBB0_146
	ds_read_u16 v57, v224 offset:35344
	s_waitcnt lgkmcnt(0)
	v_lshlrev_b32_e32 v57, 16, v57
	v_fmac_f32_e32 v71, v147, v57
	s_and_b64 vcc, exec, s[18:19]
	v_fmac_f32_e32 v75, v67, v56
	s_cbranch_vccz .LBB0_147

; __device__ __forceinline__ float bf2f(unsigned h) { return __uint_as_float(h << 16); }
; __device__ __forceinline__ unsigned pk2(float lo, float hi) { const f32x2_t v = {lo, hi}; return __builtin_bit_cast(unsigned, __builtin_convertvector(v, bf16x2_t)); }
; #define LDS_BAR() do { asm volatile("s_waitcnt lgkmcnt(0)" ::: "memory"); __builtin_amdgcn_s_barrier(); asm volatile("" ::: "memory"); } while (0)
; template <bool ISM>
; __device__ void scan_item(const Params& p, int l, int item, unsigned char* lds) {
;     ...
;           for (int j = 0; j < 4; ++j) { const int tl = fq * 4 + j, t = 16 * wid + tl; const float wi = f_wi[t];
;               float inv = 1.f;
;               if (ISM) { const float qn = __shfl(ia[NT - 1][j], lane & 48, 64); const float dn = __shfl(dsum, tl, 64); inv = __builtin_amdgcn_rcpf(fmaxf(fabsf(wi * qn + dn), f_em[t])); }
;               u16* dst = obase + (size_t)od[j];
;               float v[4];
; #pragma unroll
;               for (int n = 0; n < 4; ++n) { v[n] = (wi * ia[n][j] + ib[n][j]) * inv; if (!ISM && dir == 0) v[n] += Dh * bf2f(Vs[t * LDV + n * 16 + fr]); }
;               const unsigned p01 = pk2(v[0], v[1]), p23 = pk2(v[2], v[3]);
;               dst[0] = (u16)(p01 & 0xFFFFu); dst[16] = (u16)(p01 >> 16); dst[32] = (u16)(p23 & 0xFFFFu); dst[48] = (u16)(p23 >> 16); } }
;         LDS_BAR();
.LBB0_162:
	v_or_b32_e32 v98, v209, v228
	v_or_b32_e32 v102, v209, v153
	v_add_f32_e32 v97, v120, v121
	v_lshlrev_b32_e32 v112, 2, v98
	v_lshlrev_b32_e32 v102, 2, v102
	ds_read_b128 v[98:101], v185
	ds_bpermute_b32 v92, v112, v92
	ds_bpermute_b32 v106, v102, v97
	ds_read_b128 v[102:105], v187
	v_mov_b32_e32 v107, v68
	v_mov_b32_e32 v108, v84
	v_mov_b32_e32 v109, v88
	s_waitcnt lgkmcnt(1)
	v_fmac_f32_e32 v106, v98, v92
	s_waitcnt lgkmcnt(0)
	v_max_f32_e32 v92, v102, v102
	v_max_f32_e64 v92, |v106|, v92
	v_rcp_f32_e32 v92, v92
	v_mov_b32_e32 v106, v64
	v_pk_fma_f32 v[106:107], v[106:107], v[98:99], v[108:109] op_sel_hi:[1,0,1]
	v_mov_b32_e32 v108, v72
	v_mov_b32_e32 v109, v76
	v_mov_b32_e32 v110, v60
	v_mov_b32_e32 v111, v80
	v_pk_fma_f32 v[108:109], v[108:109], v[98:99], v[110:111] op_sel_hi:[1,0,1]
	v_mov_b32_e32 v201, v149
	v_pk_mul_f32 v[106:107], v[106:107], v[92:93] op_sel_hi:[1,0]
	v_pk_mul_f32 v[108:109], v[108:109], v[92:93] op_sel_hi:[1,0]
	v_lshl_add_u64 v[110:111], v[200:201], 1, s[28:29]
	v_cvt_pk_bf16_f32 v60, v106, v107
	v_cvt_pk_bf16_f32 v64, v108, v109
	v_mov_b32_e32 v244, v60
	v_mov_b32_e32 v245, v64
	v_or_b32_e32 v64, v209, v189
	v_lshlrev_b32_e32 v64, 2, v64
	ds_bpermute_b32 v60, v112, v93
	ds_bpermute_b32 v64, v64, v97
	v_mov_b32_e32 v68, v65
	v_mov_b32_e32 v88, v85
	v_mov_b32_e32 v76, v73
	v_mov_b32_e32 v80, v61
	s_waitcnt lgkmcnt(0)
	v_fmac_f32_e32 v64, v99, v60
	v_max_f32_e32 v60, v103, v103
	v_max_f32_e64 v60, |v64|, v60
	v_rcp_f32_e32 v60, v60
	v_pk_fma_f32 v[64:65], v[68:69], v[98:99], v[88:89] op_sel:[0,1,0]
	v_pk_fma_f32 v[68:69], v[76:77], v[98:99], v[80:81] op_sel:[0,1,0]
	v_mov_b32_e32 v199, v149
	v_pk_mul_f32 v[64:65], v[64:65], v[60:61] op_sel_hi:[1,0]
	v_pk_mul_f32 v[60:61], v[68:69], v[60:61] op_sel_hi:[1,0]
	v_lshl_add_u64 v[68:69], v[198:199], 1, s[28:29]
	v_cvt_pk_bf16_f32 v60, v60, v61
	v_or_b32_e32 v61, v209, v177
	v_cvt_pk_bf16_f32 v64, v64, v65
	v_lshlrev_b32_e32 v61, 2, v61
	v_mov_b32_e32 v246, v64
	v_mov_b32_e32 v247, v60
	ds_bpermute_b32 v60, v112, v94
	ds_bpermute_b32 v61, v61, v97
	v_mov_b32_e32 v64, v66
	v_mov_b32_e32 v65, v70
	v_mov_b32_e32 v68, v86
	v_mov_b32_e32 v69, v90
	s_waitcnt lgkmcnt(0)
	v_fmac_f32_e32 v61, v100, v60
	v_max_f32_e32 v60, v104, v104
	v_max_f32_e64 v60, |v61|, v60
	v_rcp_f32_e32 v60, v60
	v_pk_fma_f32 v[64:65], v[64:65], v[100:101], v[68:69] op_sel_hi:[1,0,1]
	v_mov_b32_e32 v68, v74
	v_mov_b32_e32 v69, v78
	v_mov_b32_e32 v72, v62
	v_mov_b32_e32 v73, v82
	v_pk_fma_f32 v[68:69], v[68:69], v[100:101], v[72:73] op_sel_hi:[1,0,1]
	v_pk_mul_f32 v[64:65], v[64:65], v[60:61] op_sel_hi:[1,0]
	v_pk_mul_f32 v[60:61], v[68:69], v[60:61] op_sel_hi:[1,0]
	v_sub_f32_e32 v96, v191, v197
	v_add_f32_e32 v191, v195, v197
	v_mov_b32_e32 v197, v149
	v_cvt_pk_bf16_f32 v60, v60, v61
	v_or_b32_e32 v61, v209, v179
	v_lshl_add_u64 v[68:69], v[196:197], 1, s[28:29]
	v_cvt_pk_bf16_f32 v62, v64, v65
	v_lshlrev_b32_e32 v61, 2, v61
	v_mov_b32_e32 v248, v62
	v_mov_b32_e32 v249, v60
	ds_bpermute_b32 v60, v112, v95
	ds_bpermute_b32 v61, v61, v97
	v_mul_f32_e32 v96, 0x3fb8aa3b, v96
	v_mov_b32_e32 v70, v67
	v_mov_b32_e32 v62, v101
	v_mov_b32_e32 v90, v87
	s_waitcnt lgkmcnt(0)
	v_fmac_f32_e32 v61, v101, v60
	v_max_f32_e32 v60, v105, v105
	v_max_f32_e64 v60, |v61|, v60
	v_rcp_f32_e32 v60, v60
	v_exp_f32_e32 v96, v96
	v_pk_fma_f32 v[64:65], v[70:71], v[62:63], v[90:91] op_sel_hi:[1,0,1]
	v_mov_b32_e32 v78, v75
	v_mov_b32_e32 v82, v63
	v_mov_b32_e32 v195, v149
	v_pk_mul_f32 v[64:65], v[64:65], v[60:61] op_sel_hi:[1,0]
	v_pk_fma_f32 v[62:63], v[78:79], v[62:63], v[82:83] op_sel_hi:[1,0,1]
	v_cvt_pk_bf16_f32 v64, v64, v65
	v_pk_mul_f32 v[60:61], v[62:63], v[60:61] op_sel_hi:[1,0]
	v_lshl_add_u64 v[62:63], v[194:195], 1, s[28:29]
	v_cvt_pk_bf16_f32 v60, v60, v61
	v_mov_b32_e32 v250, v64
	v_mov_b32_e32 v251, v60
	v_and_b32_e32 v113, 3, v208
	v_mul_u32_u24_e32 v115, 15, v113
	v_and_b32_e32 v114, 1, v208
	v_mov_b32_e32 v122, 0x5040100
	v_mov_b32_e32 v123, 0x3020706
	v_cmp_eq_u32_e32 vcc, 1, v114
	s_nop 1
	v_cndmask_b32_e32 v148, v122, v123, vcc
	v_cmp_gt_u32_e32 vcc, 2, v113
	s_nop 1
	v_cndmask_b32_e32 v113, v244, v245, vcc
	s_nop 1
	v_mov_b32_dpp v114, v113 quad_perm:[2,3,0,1] row_mask:0xf bank_mask:0xf
	v_cndmask_b32_e32 v122, v114, v244, vcc
	v_cndmask_b32_e32 v123, v245, v114, vcc
	s_nop 1
	v_mov_b32_dpp v252, v122 quad_perm:[1,0,3,2] row_mask:0xf bank_mask:0xf
	v_mov_b32_dpp v253, v123 quad_perm:[1,0,3,2] row_mask:0xf bank_mask:0xf
	v_perm_b32 v252, v252, v122, v148
	v_perm_b32 v253, v253, v123, v148
	v_add_u32_e32 v122, v115, v200
	v_mov_b32_e32 v123, v149
	v_lshl_add_u64 v[122:123], v[122:123], 1, s[28:29]
	global_store_dwordx2 v[122:123], v[252:253], off
	v_cndmask_b32_e32 v113, v246, v247, vcc
	s_nop 1
	v_mov_b32_dpp v114, v113 quad_perm:[2,3,0,1] row_mask:0xf bank_mask:0xf
	v_cndmask_b32_e32 v122, v114, v246, vcc
	v_cndmask_b32_e32 v123, v247, v114, vcc
	s_nop 1
	v_mov_b32_dpp v252, v122 quad_perm:[1,0,3,2] row_mask:0xf bank_mask:0xf
	v_mov_b32_dpp v253, v123 quad_perm:[1,0,3,2] row_mask:0xf bank_mask:0xf
	v_perm_b32 v252, v252, v122, v148
	v_perm_b32 v253, v253, v123, v148
	v_add_u32_e32 v122, v115, v198
	v_mov_b32_e32 v123, v149
	v_lshl_add_u64 v[122:123], v[122:123], 1, s[28:29]
	global_store_dwordx2 v[122:123], v[252:253], off
	v_cndmask_b32_e32 v113, v248, v249, vcc
	s_nop 1
	v_mov_b32_dpp v114, v113 quad_perm:[2,3,0,1] row_mask:0xf bank_mask:0xf
	v_cndmask_b32_e32 v122, v114, v248, vcc
	v_cndmask_b32_e32 v123, v249, v114, vcc
	s_nop 1
	v_mov_b32_dpp v252, v122 quad_perm:[1,0,3,2] row_mask:0xf bank_mask:0xf
	v_mov_b32_dpp v253, v123 quad_perm:[1,0,3,2] row_mask:0xf bank_mask:0xf
	v_perm_b32 v252, v252, v122, v148
	v_perm_b32 v253, v253, v123, v148
	v_add_u32_e32 v122, v115, v196
	v_mov_b32_e32 v123, v149
	v_lshl_add_u64 v[122:123], v[122:123], 1, s[28:29]
	global_store_dwordx2 v[122:123], v[252:253], off
	v_cndmask_b32_e32 v113, v250, v251, vcc
	s_nop 1
	v_mov_b32_dpp v114, v113 quad_perm:[2,3,0,1] row_mask:0xf bank_mask:0xf
	v_cndmask_b32_e32 v122, v114, v250, vcc
	v_cndmask_b32_e32 v123, v251, v114, vcc
	s_nop 1
	v_mov_b32_dpp v252, v122 quad_perm:[1,0,3,2] row_mask:0xf bank_mask:0xf
	v_mov_b32_dpp v253, v123 quad_perm:[1,0,3,2] row_mask:0xf bank_mask:0xf
	v_perm_b32 v252, v252, v122, v148
	v_perm_b32 v253, v253, v123, v148
	v_add_u32_e32 v122, v115, v194
	v_mov_b32_e32 v123, v149
	v_lshl_add_u64 v[122:123], v[122:123], 1, s[28:29]
	global_store_dwordx2 v[122:123], v[252:253], off
	s_waitcnt lgkmcnt(0)
	s_barrier
; __device__ __forceinline__ unsigned pk2(float lo, float hi) { const f32x2_t v = {lo, hi}; return __builtin_bit_cast(unsigned, __builtin_convertvector(v, bf16x2_t)); }
; #define LDS_BAR() do { asm volatile("s_waitcnt lgkmcnt(0)" ::: "memory"); __builtin_amdgcn_s_barrier(); asm volatile("" ::: "memory"); } while (0)
; template <bool ISM>
; __device__ void scan_item(const Params& p, int l, int item, unsigned char* lds) {
;     ...
;         LDS_BAR();
;         {
; #pragma unroll
;           for (int m = 0; m < NT; ++m) st[m] *= decay;
;     ...
;           SCAN_ST(0) SCAN_ST(1) SCAN_ST(2) SCAN_ST(3)
;     ...
; #pragma unroll
;           for (int m = 0; m < NT; ++m) { const unsigned p01 = pk2(st[m][0], st[m][1]), p23 = pk2(st[m][2], st[m][3]);
;               u16* cp = CT + (m * 16 + fq * 4) * LDK + 16 * wid + fr;
;               cp[0] = (u16)(p01 & 0xFFFFu); cp[LDK] = (u16)(p01 >> 16); cp[2 * LDK] = (u16)(p23 & 0xFFFFu); cp[3 * LDK] = (u16)(p23 >> 16); } }
;         LDS_BAR();
	v_pk_mul_f32 v[18:19], v[18:19], v[96:97] op_sel_hi:[1,0]
	v_pk_mul_f32 v[16:17], v[16:17], v[96:97] op_sel_hi:[1,0]
	v_pk_mul_f32 v[22:23], v[22:23], v[96:97] op_sel_hi:[1,0]
	v_pk_mul_f32 v[20:21], v[20:21], v[96:97] op_sel_hi:[1,0]
	ds_read_b64_tr_b16 v[80:81], v159 offset:0
	ds_read_b64_tr_b16 v[82:83], v159 offset:0x440
	ds_read_b64_tr_b16 v[76:77], v161 offset:0
	ds_read_b64_tr_b16 v[78:79], v161 offset:0x2c0
	ds_read_b64_tr_b16 v[72:73], v161 offset:32
	ds_read_b64_tr_b16 v[74:75], v161 offset:0x2e0
	ds_read_b64_tr_b16 v[68:69], v161 offset:64
	ds_read_b64_tr_b16 v[70:71], v161 offset:0x300
	ds_read_b64_tr_b16 v[64:65], v161 offset:0x60
	ds_read_b64_tr_b16 v[66:67], v161 offset:0x320
	ds_read_b64_tr_b16 v[60:61], v161 offset:0x80
	ds_read_b64_tr_b16 v[62:63], v161 offset:0x340
	s_waitcnt lgkmcnt(0)
	v_pk_mul_f32 v[26:27], v[26:27], v[96:97] op_sel_hi:[1,0]
	v_mfma_f32_16x16x32_bf16 v[16:19], v[76:79], v[80:83], v[16:19]
	v_mul_f32_e64 v24, v24, v96
	v_mul_f32_e64 v25, v25, v96
	v_pk_mul_f32 v[30:31], v[30:31], v[96:97] op_sel_hi:[1,0]
	v_pk_mul_f32 v[28:29], v[28:29], v[96:97] op_sel_hi:[1,0]
	v_mfma_f32_16x16x32_bf16 v[20:23], v[72:75], v[80:83], v[20:23]
	v_mul_f32_e64 v34, v34, v96
	v_mul_f32_e64 v35, v35, v96
	v_pk_mul_f32 v[32:33], v[32:33], v[96:97] op_sel_hi:[1,0]
	s_add_i32 s63, s63, -1
	v_mfma_f32_16x16x32_bf16 v[24:27], v[68:71], v[80:83], v[24:27]
	s_cmp_eq_u32 s63, -1
	v_mov_b32_e32 v200, v241
	v_mov_b32_e32 v198, v240
	v_mfma_f32_16x16x32_bf16 v[28:31], v[64:67], v[80:83], v[28:31]
	v_mov_b32_e32 v196, v239
	v_mov_b32_e32 v194, v238
	s_waitcnt vmcnt(5)
	v_mov_b32_e32 v195, v242
	v_mfma_f32_16x16x32_bf16 v[32:35], v[60:63], v[80:83], v[32:35]
	ds_read_b64_tr_b16 v[80:81], v159 offset:0x2200
	ds_read_b64_tr_b16 v[82:83], v159 offset:0x2640
	ds_read_b64_tr_b16 v[76:77], v161 offset:0x1600
	ds_read_b64_tr_b16 v[78:79], v161 offset:0x18c0
	ds_read_b64_tr_b16 v[72:73], v161 offset:0x1620
	ds_read_b64_tr_b16 v[74:75], v161 offset:0x18e0
	ds_read_b64_tr_b16 v[68:69], v161 offset:0x1640
	ds_read_b64_tr_b16 v[70:71], v161 offset:0x1900
	ds_read_b64_tr_b16 v[64:65], v161 offset:0x1660
	ds_read_b64_tr_b16 v[66:67], v161 offset:0x1920
	ds_read_b64_tr_b16 v[60:61], v161 offset:0x1680
	ds_read_b64_tr_b16 v[62:63], v161 offset:0x1940
	s_waitcnt lgkmcnt(0)
	s_nop 0
	v_mfma_f32_16x16x32_bf16 v[16:19], v[76:79], v[80:83], v[16:19]
	v_mfma_f32_16x16x32_bf16 v[20:23], v[72:75], v[80:83], v[20:23]
	v_mfma_f32_16x16x32_bf16 v[24:27], v[68:71], v[80:83], v[24:27]
	v_mfma_f32_16x16x32_bf16 v[28:31], v[64:67], v[80:83], v[28:31]
	v_mfma_f32_16x16x32_bf16 v[32:35], v[60:63], v[80:83], v[32:35]
	ds_read_b64_tr_b16 v[80:81], v159 offset:0x4400
	ds_read_b64_tr_b16 v[82:83], v159 offset:0x4840
	ds_read_b64_tr_b16 v[76:77], v161 offset:0x2c00
	ds_read_b64_tr_b16 v[78:79], v161 offset:0x2ec0
	ds_read_b64_tr_b16 v[72:73], v161 offset:0x2c20
	ds_read_b64_tr_b16 v[74:75], v161 offset:0x2ee0
	ds_read_b64_tr_b16 v[68:69], v161 offset:0x2c40
	ds_read_b64_tr_b16 v[70:71], v161 offset:0x2f00
	ds_read_b64_tr_b16 v[64:65], v161 offset:0x2c60
	ds_read_b64_tr_b16 v[66:67], v161 offset:0x2f20
	ds_read_b64_tr_b16 v[60:61], v161 offset:0x2c80
	ds_read_b64_tr_b16 v[62:63], v161 offset:0x2f40
	s_waitcnt lgkmcnt(0)
	s_nop 0
	v_mfma_f32_16x16x32_bf16 v[16:19], v[76:79], v[80:83], v[16:19]
	v_mfma_f32_16x16x32_bf16 v[20:23], v[72:75], v[80:83], v[20:23]
	v_mfma_f32_16x16x32_bf16 v[24:27], v[68:71], v[80:83], v[24:27]
	v_mfma_f32_16x16x32_bf16 v[28:31], v[64:67], v[80:83], v[28:31]
	v_mfma_f32_16x16x32_bf16 v[32:35], v[60:63], v[80:83], v[32:35]
	ds_read_b64_tr_b16 v[80:81], v159 offset:0x6600
	ds_read_b64_tr_b16 v[82:83], v159 offset:0x6a40
	ds_read_b64_tr_b16 v[76:77], v161 offset:0x4200
	ds_read_b64_tr_b16 v[78:79], v161 offset:0x44c0
	ds_read_b64_tr_b16 v[72:73], v161 offset:0x4220
	ds_read_b64_tr_b16 v[74:75], v161 offset:0x44e0
	ds_read_b64_tr_b16 v[68:69], v161 offset:0x4240
	ds_read_b64_tr_b16 v[70:71], v161 offset:0x4500
	ds_read_b64_tr_b16 v[64:65], v161 offset:0x4260
	ds_read_b64_tr_b16 v[66:67], v161 offset:0x4520
	ds_read_b64_tr_b16 v[60:61], v161 offset:0x4280
	ds_read_b64_tr_b16 v[62:63], v161 offset:0x4540
	s_waitcnt lgkmcnt(0)
	s_nop 0
	v_mfma_f32_16x16x32_bf16 v[16:19], v[76:79], v[80:83], v[16:19]
	v_mov_b64_e32 v[78:79], v[58:59]
	v_mov_b64_e32 v[76:77], v[56:57]
	v_mfma_f32_16x16x32_bf16 v[20:23], v[72:75], v[80:83], v[20:23]
	v_mov_b64_e32 v[74:75], v[50:51]
	v_mov_b64_e32 v[72:73], v[48:49]
	v_mfma_f32_16x16x32_bf16 v[24:27], v[68:71], v[80:83], v[24:27]
	v_mov_b64_e32 v[70:71], v[46:47]
	v_mov_b64_e32 v[68:69], v[44:45]
	v_mfma_f32_16x16x32_bf16 v[28:31], v[64:67], v[80:83], v[28:31]
	v_mov_b64_e32 v[66:67], v[42:43]
	v_mov_b64_e32 v[64:65], v[40:41]
	v_mfma_f32_16x16x32_bf16 v[32:35], v[60:63], v[80:83], v[32:35]
	v_cvt_pk_bf16_f32 v60, v16, v17
	v_cvt_pk_bf16_f32 v61, v18, v19
	ds_write_b16 v235, v60
	ds_write_b16_d16_hi v235, v60 offset:272
	ds_write_b16 v235, v61 offset:544
	ds_write_b16_d16_hi v235, v61 offset:816
	v_cvt_pk_bf16_f32 v60, v20, v21
	v_cvt_pk_bf16_f32 v61, v22, v23
	ds_write_b16 v235, v60 offset:4352
	ds_write_b16_d16_hi v235, v60 offset:4624
	ds_write_b16 v235, v61 offset:4896
	ds_write_b16_d16_hi v235, v61 offset:5168
	v_cvt_pk_bf16_f32 v60, v24, v25
	v_cvt_pk_bf16_f32 v61, v26, v27
	ds_write_b16 v235, v60 offset:8704
	ds_write_b16_d16_hi v235, v60 offset:8976
	ds_write_b16 v235, v61 offset:9248
	ds_write_b16_d16_hi v235, v61 offset:9520
	v_cvt_pk_bf16_f32 v60, v28, v29
	v_cvt_pk_bf16_f32 v61, v30, v31
	ds_write_b16 v235, v60 offset:13056
	ds_write_b16_d16_hi v235, v60 offset:13328
	ds_write_b16 v235, v61 offset:13600
	ds_write_b16_d16_hi v235, v61 offset:13872
	v_cvt_pk_bf16_f32 v60, v32, v33
	v_cvt_pk_bf16_f32 v61, v34, v35
	ds_write_b16 v235, v60 offset:17408
	ds_write_b16_d16_hi v235, v60 offset:17680
	ds_write_b16 v235, v61 offset:17952
	ds_write_b16_d16_hi v235, v61 offset:18224
	s_waitcnt lgkmcnt(0)
	s_barrier
	v_mov_b64_e32 v[82:83], v[54:55]
	v_mov_b64_e32 v[62:63], v[38:39]
	v_mov_b64_e32 v[80:81], v[52:53]
	v_mov_b64_e32 v[60:61], v[36:37]
	s_cbranch_scc1 .LBB0_18
